# last XCC leader no longer bumps the (now unread) generation word
# baseline (speedup 1.0000x reference)
.LBB0_115:
	s_or_b64 exec, exec, s[10:11]
	v_cvt_f32_u32_e32 v3, v0
	s_waitcnt vmcnt(0)
	v_readfirstlane_b32 s3, v2
	s_add_u32 s10, s78, 0x3500
	s_addc_u32 s11, s79, 0
	v_rcp_iflag_f32_e32 v3, v3
	v_add_u32_e32 v1, s3, v1
	v_add_u32_e32 v4, 1, v1
	s_mov_b64 s[12:13], 0
	v_mul_f32_e32 v2, 0x4f7ffffe, v3
	v_cvt_u32_f32_e32 v2, v2
	v_sub_u32_e32 v3, 0, v0
	v_mul_lo_u32 v3, v3, v2
	v_mul_hi_u32 v3, v2, v3
	v_add_u32_e32 v2, v2, v3
	v_mul_hi_u32 v2, v1, v2
	v_mul_lo_u32 v3, v2, v0
	v_sub_u32_e32 v1, v1, v3
	v_add_u32_e32 v5, 1, v2
	v_cmp_ge_u32_e32 vcc, v1, v0
	v_sub_u32_e32 v3, v1, v0
	s_nop 0
	v_cndmask_b32_e32 v2, v2, v5, vcc
	v_cndmask_b32_e32 v1, v1, v3, vcc
	v_add_u32_e32 v3, 1, v2
	v_cmp_ge_u32_e32 vcc, v1, v0
	s_nop 1
	v_cndmask_b32_e32 v2, v2, v3, vcc
	v_mul_lo_u32 v1, v0, v2
	v_add_u32_e32 v0, v1, v0
	v_cmp_ne_u32_e32 vcc, v4, v0
	v_mov_b64_e32 v[0:1], s[10:11]
	s_and_saveexec_b64 s[8:9], vcc
	s_cbranch_execz .LBB0_127
	v_mov_b32_e32 v0, 0
	global_load_dword v1, v0, s[10:11] offset:-256 sc1
	s_mov_b64 s[16:17], 0
	s_waitcnt vmcnt(0)
	v_mov_b32_e32 v238, 0x20004
	ds_read_b32 v238, v238
	s_waitcnt lgkmcnt(0)
	v_add_u32_e32 v2, 1, v2
	v_mul_lo_u32 v2, v2, v238
	v_cmp_lt_u32_e32 vcc, v1, v2
	s_and_saveexec_b64 s[14:15], vcc
	s_cbranch_execz .LBB0_126
	s_add_u32 s12, s78, 0x200
	s_addc_u32 s13, s79, 0
	s_mov_b32 s3, 1
	s_branch .LBB0_119

.LBB0_188:
	s_or_b64 exec, exec, s[8:9]
	v_cvt_f32_u32_e32 v3, v0
	s_waitcnt vmcnt(0)
	v_readfirstlane_b32 s6, v2
	s_add_u32 s8, s78, 0x3500
	s_addc_u32 s9, s79, 0
	v_rcp_iflag_f32_e32 v3, v3
	v_add_u32_e32 v1, s6, v1
	v_add_u32_e32 v4, 1, v1
	s_mov_b64 s[10:11], 0
	v_mul_f32_e32 v2, 0x4f7ffffe, v3
	v_cvt_u32_f32_e32 v2, v2
	v_sub_u32_e32 v3, 0, v0
	v_mul_lo_u32 v3, v3, v2
	v_mul_hi_u32 v3, v2, v3
	v_add_u32_e32 v2, v2, v3
	v_mul_hi_u32 v2, v1, v2
	v_mul_lo_u32 v3, v2, v0
	v_sub_u32_e32 v1, v1, v3
	v_add_u32_e32 v5, 1, v2
	v_cmp_ge_u32_e32 vcc, v1, v0
	v_sub_u32_e32 v3, v1, v0
	s_nop 0
	v_cndmask_b32_e32 v2, v2, v5, vcc
	v_cndmask_b32_e32 v1, v1, v3, vcc
	v_add_u32_e32 v3, 1, v2
	v_cmp_ge_u32_e32 vcc, v1, v0
	s_nop 1
	v_cndmask_b32_e32 v2, v2, v3, vcc
	v_mul_lo_u32 v1, v0, v2
	v_add_u32_e32 v0, v1, v0
	v_cmp_ne_u32_e32 vcc, v4, v0
	v_mov_b64_e32 v[0:1], s[8:9]
	s_and_saveexec_b64 s[6:7], vcc
	s_cbranch_execz .LBB0_200
	v_mov_b32_e32 v0, 0
	global_load_dword v1, v0, s[8:9] offset:-256 sc1
	s_mov_b64 s[14:15], 0
	s_waitcnt vmcnt(0)
	v_mov_b32_e32 v238, 0x20004
	ds_read_b32 v238, v238
	s_waitcnt lgkmcnt(0)
	v_add_u32_e32 v2, 1, v2
	v_mul_lo_u32 v2, v2, v238
	v_cmp_lt_u32_e32 vcc, v1, v2
	s_cmp_lt_u32 s2, 16
	s_cbranch_scc0 ATB0_4007
	v_readfirstlane_b32 s100, v2
	s_mov_b64 vcc, 0

.LBB0_343:
	s_or_b64 exec, exec, s[8:9]
	v_cvt_f32_u32_e32 v3, v0
	s_waitcnt vmcnt(0)
	v_readfirstlane_b32 s6, v2
	s_add_u32 s8, s78, 0x3500
	s_addc_u32 s9, s79, 0
	v_rcp_iflag_f32_e32 v3, v3
	v_add_u32_e32 v1, s6, v1
	v_add_u32_e32 v4, 1, v1
	s_mov_b64 s[10:11], 0
	v_mul_f32_e32 v2, 0x4f7ffffe, v3
	v_cvt_u32_f32_e32 v2, v2
	v_sub_u32_e32 v3, 0, v0
	v_mul_lo_u32 v3, v3, v2
	v_mul_hi_u32 v3, v2, v3
	v_add_u32_e32 v2, v2, v3
	v_mul_hi_u32 v2, v1, v2
	v_mul_lo_u32 v3, v2, v0
	v_sub_u32_e32 v1, v1, v3
	v_add_u32_e32 v5, 1, v2
	v_cmp_ge_u32_e32 vcc, v1, v0
	v_sub_u32_e32 v3, v1, v0
	s_nop 0
	v_cndmask_b32_e32 v2, v2, v5, vcc
	v_cndmask_b32_e32 v1, v1, v3, vcc
	v_add_u32_e32 v3, 1, v2
	v_cmp_ge_u32_e32 vcc, v1, v0
	s_nop 1
	v_cndmask_b32_e32 v2, v2, v3, vcc
	v_mul_lo_u32 v1, v0, v2
	v_add_u32_e32 v0, v1, v0
	v_cmp_ne_u32_e32 vcc, v4, v0
	v_mov_b64_e32 v[0:1], s[8:9]
	s_and_saveexec_b64 s[6:7], vcc
	s_cbranch_execz .LBB0_355
	v_mov_b32_e32 v0, 0
	global_load_dword v1, v0, s[8:9] offset:-256 sc1
	s_mov_b64 s[14:15], 0
	s_waitcnt vmcnt(0)
	v_mov_b32_e32 v238, 0x20004
	ds_read_b32 v238, v238
	s_waitcnt lgkmcnt(0)
	v_add_u32_e32 v2, 1, v2
	v_mul_lo_u32 v2, v2, v238
	v_cmp_lt_u32_e32 vcc, v1, v2
	s_and_saveexec_b64 s[12:13], vcc
	s_cbranch_execz .LBB0_354
	s_add_u32 s10, s78, 0x200
	s_addc_u32 s11, s79, 0
	s_mov_b32 s26, 1
	s_branch .LBB0_347

.LBB0_428:
	s_or_b64 exec, exec, s[8:9]
	s_waitcnt vmcnt(0)
	v_readfirstlane_b32 s6, v2
	v_cvt_f32_u32_e32 v2, v0
	v_sub_u32_e32 v3, 0, v0
	v_add_u32_e32 v1, s6, v1
	s_add_u32 s6, s78, 0x3500
	v_rcp_iflag_f32_e32 v2, v2
	s_addc_u32 s7, s79, 0
	s_mov_b64 s[10:11], 0
	v_mul_f32_e32 v2, 0x4f7ffffe, v2
	v_cvt_u32_f32_e32 v2, v2
	v_mul_lo_u32 v3, v3, v2
	v_mul_hi_u32 v3, v2, v3
	v_add_u32_e32 v2, v2, v3
	v_mul_hi_u32 v2, v1, v2
	v_mul_lo_u32 v3, v2, v0
	v_sub_u32_e32 v3, v1, v3
	v_cmp_ge_u32_e32 vcc, v3, v0
	v_add_u32_e32 v4, 1, v2
	v_add_u32_e32 v1, 1, v1
	v_cndmask_b32_e32 v2, v2, v4, vcc
	v_sub_u32_e32 v4, v3, v0
	v_cndmask_b32_e32 v3, v3, v4, vcc
	v_cmp_ge_u32_e32 vcc, v3, v0
	v_add_u32_e32 v3, 1, v2
	s_nop 0
	v_cndmask_b32_e32 v2, v2, v3, vcc
	v_mul_lo_u32 v3, v0, v2
	v_add_u32_e32 v0, v3, v0
	v_cmp_ne_u32_e32 vcc, v1, v0
	v_mov_b64_e32 v[0:1], s[6:7]
	s_and_saveexec_b64 s[8:9], vcc
	s_cbranch_execz .LBB0_440
	v_mov_b32_e32 v0, 0
	global_load_dword v1, v0, s[6:7] offset:-256 sc1
	s_mov_b64 s[14:15], 0
	s_waitcnt vmcnt(0)
	v_mov_b32_e32 v238, 0x20004
	ds_read_b32 v238, v238
	s_waitcnt lgkmcnt(0)
	v_add_u32_e32 v2, 1, v2
	v_mul_lo_u32 v2, v2, v238
	v_cmp_lt_u32_e32 vcc, v1, v2
	s_and_saveexec_b64 s[12:13], vcc
	s_cbranch_execz .LBB0_439
	s_add_u32 s10, s78, 0x200
	s_addc_u32 s11, s79, 0
	s_mov_b32 s26, 1
	s_branch .LBB0_432

.LBB0_501:
	s_or_b64 exec, exec, s[8:9]
	s_waitcnt vmcnt(0)
	v_readfirstlane_b32 s6, v2
	v_cvt_f32_u32_e32 v2, v0
	v_sub_u32_e32 v3, 0, v0
	v_add_u32_e32 v1, s6, v1
	s_add_u32 s6, s78, 0x3500
	v_rcp_iflag_f32_e32 v2, v2
	s_addc_u32 s7, s79, 0
	s_mov_b64 s[10:11], 0
	v_mul_f32_e32 v2, 0x4f7ffffe, v2
	v_cvt_u32_f32_e32 v2, v2
	v_mul_lo_u32 v3, v3, v2
	v_mul_hi_u32 v3, v2, v3
	v_add_u32_e32 v2, v2, v3
	v_mul_hi_u32 v2, v1, v2
	v_mul_lo_u32 v3, v2, v0
	v_sub_u32_e32 v3, v1, v3
	v_cmp_ge_u32_e32 vcc, v3, v0
	v_add_u32_e32 v4, 1, v2
	v_add_u32_e32 v1, 1, v1
	v_cndmask_b32_e32 v2, v2, v4, vcc
	v_sub_u32_e32 v4, v3, v0
	v_cndmask_b32_e32 v3, v3, v4, vcc
	v_cmp_ge_u32_e32 vcc, v3, v0
	v_add_u32_e32 v3, 1, v2
	s_nop 0
	v_cndmask_b32_e32 v2, v2, v3, vcc
	v_mul_lo_u32 v3, v0, v2
	v_add_u32_e32 v0, v3, v0
	v_cmp_ne_u32_e32 vcc, v1, v0
	v_mov_b64_e32 v[0:1], s[6:7]
	s_and_saveexec_b64 s[8:9], vcc
	s_cbranch_execz .LBB0_513
	v_mov_b32_e32 v0, 0
	global_load_dword v1, v0, s[6:7] offset:-256 sc1
	s_mov_b64 s[14:15], 0
	s_waitcnt vmcnt(0)
	v_mov_b32_e32 v238, 0x20004
	ds_read_b32 v238, v238
	s_waitcnt lgkmcnt(0)
	v_add_u32_e32 v2, 1, v2
	v_mul_lo_u32 v2, v2, v238
	v_cmp_lt_u32_e32 vcc, v1, v2
	s_and_saveexec_b64 s[12:13], vcc
	s_cbranch_execz .LBB0_512
	s_add_u32 s10, s78, 0x200
	s_addc_u32 s11, s79, 0
	s_mov_b32 s24, 1
	s_branch .LBB0_505

.LBB0_897:
	s_or_b64 exec, exec, s[8:9]
	s_waitcnt vmcnt(0)
	v_readfirstlane_b32 s6, v2
	v_cvt_f32_u32_e32 v2, v0
	v_sub_u32_e32 v3, 0, v0
	v_add_u32_e32 v1, s6, v1
	s_add_u32 s6, s78, 0x3500
	v_rcp_iflag_f32_e32 v2, v2
	s_addc_u32 s7, s79, 0
	s_mov_b64 s[10:11], 0
	v_mul_f32_e32 v2, 0x4f7ffffe, v2
	v_cvt_u32_f32_e32 v2, v2
	v_mul_lo_u32 v3, v3, v2
	v_mul_hi_u32 v3, v2, v3
	v_add_u32_e32 v2, v2, v3
	v_mul_hi_u32 v2, v1, v2
	v_mul_lo_u32 v3, v2, v0
	v_sub_u32_e32 v3, v1, v3
	v_cmp_ge_u32_e32 vcc, v3, v0
	v_add_u32_e32 v4, 1, v2
	v_add_u32_e32 v1, 1, v1
	v_cndmask_b32_e32 v2, v2, v4, vcc
	v_sub_u32_e32 v4, v3, v0
	v_cndmask_b32_e32 v3, v3, v4, vcc
	v_cmp_ge_u32_e32 vcc, v3, v0
	v_add_u32_e32 v3, 1, v2
	s_nop 0
	v_cndmask_b32_e32 v2, v2, v3, vcc
	v_mul_lo_u32 v3, v0, v2
	v_add_u32_e32 v0, v3, v0
	v_cmp_ne_u32_e32 vcc, v1, v0
	v_mov_b64_e32 v[0:1], s[6:7]
	s_and_saveexec_b64 s[8:9], vcc
	s_cbranch_execz .LBB0_909
	v_mov_b32_e32 v0, 0
	global_load_dword v1, v0, s[6:7] offset:-256 sc1
	s_mov_b64 s[14:15], 0
	s_waitcnt vmcnt(0)
	v_mov_b32_e32 v238, 0x20004
	ds_read_b32 v238, v238
	s_waitcnt lgkmcnt(0)
	v_add_u32_e32 v2, 1, v2
	v_mul_lo_u32 v2, v2, v238
	v_cmp_lt_u32_e32 vcc, v1, v2
	s_cmp_lt_u32 s2, 16
	s_cbranch_scc0 ATB1_24649
	v_readfirstlane_b32 s100, v2
	s_mov_b64 vcc, 0

.LBB0_1303:
	s_or_b64 exec, exec, s[10:11]
	s_waitcnt vmcnt(0)
	v_readfirstlane_b32 s8, v2
	v_cvt_f32_u32_e32 v2, v0
	v_sub_u32_e32 v3, 0, v0
	v_add_u32_e32 v1, s8, v1
	s_add_u32 s8, s78, 0x3500
	v_rcp_iflag_f32_e32 v2, v2
	s_addc_u32 s9, s79, 0
	s_mov_b64 s[12:13], 0
	v_mul_f32_e32 v2, 0x4f7ffffe, v2
	v_cvt_u32_f32_e32 v2, v2
	v_mul_lo_u32 v3, v3, v2
	v_mul_hi_u32 v3, v2, v3
	v_add_u32_e32 v2, v2, v3
	v_mul_hi_u32 v2, v1, v2
	v_mul_lo_u32 v3, v2, v0
	v_sub_u32_e32 v3, v1, v3
	v_cmp_ge_u32_e32 vcc, v3, v0
	v_add_u32_e32 v4, 1, v2
	v_add_u32_e32 v1, 1, v1
	v_cndmask_b32_e32 v2, v2, v4, vcc
	v_sub_u32_e32 v4, v3, v0
	v_cndmask_b32_e32 v3, v3, v4, vcc
	v_cmp_ge_u32_e32 vcc, v3, v0
	v_add_u32_e32 v3, 1, v2
	s_nop 0
	v_cndmask_b32_e32 v2, v2, v3, vcc
	v_mul_lo_u32 v3, v0, v2
	v_add_u32_e32 v0, v3, v0
	v_cmp_ne_u32_e32 vcc, v1, v0
	v_mov_b64_e32 v[0:1], s[8:9]
	s_and_saveexec_b64 s[10:11], vcc
	s_cbranch_execz .LBB0_1315
	v_mov_b32_e32 v0, 0
	global_load_dword v1, v0, s[8:9] offset:-256 sc1
	s_mov_b64 s[16:17], 0
	s_waitcnt vmcnt(0)
	v_mov_b32_e32 v238, 0x20004
	ds_read_b32 v238, v238
	s_waitcnt lgkmcnt(0)
	v_add_u32_e32 v2, 1, v2
	v_mul_lo_u32 v2, v2, v238
	v_cmp_lt_u32_e32 vcc, v1, v2
	s_and_saveexec_b64 s[14:15], vcc
	s_cbranch_execz .LBB0_1314
	s_add_u32 s12, s78, 0x200
	s_addc_u32 s13, s79, 0
	s_mov_b32 s26, 1
	s_branch .LBB0_1307

.LBB0_1606:
	s_or_b64 exec, exec, s[8:9]
	s_waitcnt vmcnt(0)
	v_readfirstlane_b32 s6, v2
	v_cvt_f32_u32_e32 v2, v0
	v_sub_u32_e32 v3, 0, v0
	v_add_u32_e32 v1, s6, v1
	s_add_u32 s6, s78, 0x3500
	v_rcp_iflag_f32_e32 v2, v2
	s_addc_u32 s7, s79, 0
	s_mov_b64 s[10:11], 0
	v_mul_f32_e32 v2, 0x4f7ffffe, v2
	v_cvt_u32_f32_e32 v2, v2
	v_mul_lo_u32 v3, v3, v2
	v_mul_hi_u32 v3, v2, v3
	v_add_u32_e32 v2, v2, v3
	v_mul_hi_u32 v2, v1, v2
	v_mul_lo_u32 v3, v2, v0
	v_sub_u32_e32 v3, v1, v3
	v_cmp_ge_u32_e32 vcc, v3, v0
	v_add_u32_e32 v4, 1, v2
	v_add_u32_e32 v1, 1, v1
	v_cndmask_b32_e32 v2, v2, v4, vcc
	v_sub_u32_e32 v4, v3, v0
	v_cndmask_b32_e32 v3, v3, v4, vcc
	v_cmp_ge_u32_e32 vcc, v3, v0
	v_add_u32_e32 v3, 1, v2
	s_nop 0
	v_cndmask_b32_e32 v2, v2, v3, vcc
	v_mul_lo_u32 v3, v0, v2
	v_add_u32_e32 v0, v3, v0
	v_cmp_ne_u32_e32 vcc, v1, v0
	v_mov_b64_e32 v[0:1], s[6:7]
	s_and_saveexec_b64 s[8:9], vcc
	s_cbranch_execz .LBB0_1618
	v_mov_b32_e32 v0, 0
	global_load_dword v1, v0, s[6:7] offset:-256 sc1
	s_mov_b64 s[14:15], 0
	s_waitcnt vmcnt(0)
	v_mov_b32_e32 v238, 0x20004
	ds_read_b32 v238, v238
	s_waitcnt lgkmcnt(0)
	v_add_u32_e32 v2, 1, v2
	v_mul_lo_u32 v2, v2, v238
	v_cmp_lt_u32_e32 vcc, v1, v2
	s_cmp_lt_u32 s2, 16
	s_cbranch_scc0 ATB2_45257
	v_readfirstlane_b32 s100, v2
	s_mov_b64 vcc, 0

.LBB0_2242:
	s_or_b64 exec, exec, s[8:9]
	v_cvt_f32_u32_e32 v3, v0
	s_waitcnt vmcnt(0)
	v_readfirstlane_b32 s6, v2
	s_add_u32 s8, s78, 0x3500
	s_addc_u32 s9, s79, 0
	v_rcp_iflag_f32_e32 v3, v3
	v_add_u32_e32 v1, s6, v1
	v_add_u32_e32 v4, 1, v1
	s_mov_b64 s[10:11], 0
	v_mul_f32_e32 v2, 0x4f7ffffe, v3
	v_cvt_u32_f32_e32 v2, v2
	v_sub_u32_e32 v3, 0, v0
	v_mul_lo_u32 v3, v3, v2
	v_mul_hi_u32 v3, v2, v3
	v_add_u32_e32 v2, v2, v3
	v_mul_hi_u32 v2, v1, v2
	v_mul_lo_u32 v3, v2, v0
	v_sub_u32_e32 v1, v1, v3
	v_add_u32_e32 v5, 1, v2
	v_cmp_ge_u32_e32 vcc, v1, v0
	v_sub_u32_e32 v3, v1, v0
	s_nop 0
	v_cndmask_b32_e32 v2, v2, v5, vcc
	v_cndmask_b32_e32 v1, v1, v3, vcc
	v_add_u32_e32 v3, 1, v2
	v_cmp_ge_u32_e32 vcc, v1, v0
	s_nop 1
	v_cndmask_b32_e32 v2, v2, v3, vcc
	v_mul_lo_u32 v1, v0, v2
	v_add_u32_e32 v0, v1, v0
	v_cmp_ne_u32_e32 vcc, v4, v0
	v_mov_b64_e32 v[0:1], s[8:9]
	s_and_saveexec_b64 s[6:7], vcc
	s_cbranch_execz .LBB0_2254
	v_mov_b32_e32 v0, 0
	global_load_dword v1, v0, s[8:9] offset:-256 sc1
	s_mov_b64 s[14:15], 0
	s_waitcnt vmcnt(0)
	v_mov_b32_e32 v238, 0x20004
	ds_read_b32 v238, v238
	s_waitcnt lgkmcnt(0)
	v_add_u32_e32 v2, 1, v2
	v_mul_lo_u32 v2, v2, v238
	v_cmp_lt_u32_e32 vcc, v1, v2
	s_and_saveexec_b64 s[12:13], vcc
	s_cbranch_execz .LBB0_2253
	s_add_u32 s10, s78, 0x200
	s_addc_u32 s11, s79, 0
	s_mov_b32 s24, 1
	s_branch .LBB0_2246

.LBB0_2315:
	s_or_b64 exec, exec, s[8:9]
	v_cvt_f32_u32_e32 v3, v0
	s_waitcnt vmcnt(0)
	v_readfirstlane_b32 s6, v2
	s_add_u32 s8, s78, 0x3500
	s_addc_u32 s9, s79, 0
	v_rcp_iflag_f32_e32 v3, v3
	v_add_u32_e32 v1, s6, v1
	v_add_u32_e32 v4, 1, v1
	s_mov_b64 s[10:11], 0
	v_mul_f32_e32 v2, 0x4f7ffffe, v3
	v_cvt_u32_f32_e32 v2, v2
	v_sub_u32_e32 v3, 0, v0
	v_mul_lo_u32 v3, v3, v2
	v_mul_hi_u32 v3, v2, v3
	v_add_u32_e32 v2, v2, v3
	v_mul_hi_u32 v2, v1, v2
	v_mul_lo_u32 v3, v2, v0
	v_sub_u32_e32 v1, v1, v3
	v_add_u32_e32 v5, 1, v2
	v_cmp_ge_u32_e32 vcc, v1, v0
	v_sub_u32_e32 v3, v1, v0
	s_nop 0
	v_cndmask_b32_e32 v2, v2, v5, vcc
	v_cndmask_b32_e32 v1, v1, v3, vcc
	v_add_u32_e32 v3, 1, v2
	v_cmp_ge_u32_e32 vcc, v1, v0
	s_nop 1
	v_cndmask_b32_e32 v2, v2, v3, vcc
	v_mul_lo_u32 v1, v0, v2
	v_add_u32_e32 v0, v1, v0
	v_cmp_ne_u32_e32 vcc, v4, v0
	v_mov_b64_e32 v[0:1], s[8:9]
	s_and_saveexec_b64 s[6:7], vcc
	s_cbranch_execz .LBB0_2327
	v_mov_b32_e32 v0, 0
	global_load_dword v1, v0, s[8:9] offset:-256 sc1
	s_mov_b64 s[14:15], 0
	s_waitcnt vmcnt(0)
	v_mov_b32_e32 v238, 0x20004
	ds_read_b32 v238, v238
	s_waitcnt lgkmcnt(0)
	v_add_u32_e32 v2, 1, v2
	v_mul_lo_u32 v2, v2, v238
	v_cmp_lt_u32_e32 vcc, v1, v2
	s_cmp_lt_u32 s2, 16
	s_cbranch_scc0 ATB3_65845
	v_readfirstlane_b32 s100, v2
	s_mov_b64 vcc, 0

.LBB0_2722:
	s_or_b64 exec, exec, s[10:11]
	v_cvt_f32_u32_e32 v3, v0
	s_waitcnt vmcnt(0)
	v_readfirstlane_b32 s6, v2
	s_add_u32 s10, s78, 0x3500
	s_addc_u32 s11, s79, 0
	v_rcp_iflag_f32_e32 v3, v3
	v_add_u32_e32 v1, s6, v1
	v_add_u32_e32 v4, 1, v1
	s_mov_b64 s[12:13], 0
	v_mul_f32_e32 v2, 0x4f7ffffe, v3
	v_cvt_u32_f32_e32 v2, v2
	v_sub_u32_e32 v3, 0, v0
	v_mul_lo_u32 v3, v3, v2
	v_mul_hi_u32 v3, v2, v3
	v_add_u32_e32 v2, v2, v3
	v_mul_hi_u32 v2, v1, v2
	v_mul_lo_u32 v3, v2, v0
	v_sub_u32_e32 v1, v1, v3
	v_add_u32_e32 v5, 1, v2
	v_cmp_ge_u32_e32 vcc, v1, v0
	v_sub_u32_e32 v3, v1, v0
	s_nop 0
	v_cndmask_b32_e32 v2, v2, v5, vcc
	v_cndmask_b32_e32 v1, v1, v3, vcc
	v_add_u32_e32 v3, 1, v2
	v_cmp_ge_u32_e32 vcc, v1, v0
	s_nop 1
	v_cndmask_b32_e32 v2, v2, v3, vcc
	v_mul_lo_u32 v1, v0, v2
	v_add_u32_e32 v0, v1, v0
	v_cmp_ne_u32_e32 vcc, v4, v0
	v_mov_b64_e32 v[0:1], s[10:11]
	s_and_saveexec_b64 s[6:7], vcc
	s_cbranch_execz .LBB0_2734
	v_mov_b32_e32 v0, 0
	global_load_dword v1, v0, s[10:11] offset:-256 sc1
	s_mov_b64 s[16:17], 0
	s_waitcnt vmcnt(0)
	v_mov_b32_e32 v238, 0x20004
	ds_read_b32 v238, v238
	s_waitcnt lgkmcnt(0)
	v_add_u32_e32 v2, 1, v2
	v_mul_lo_u32 v2, v2, v238
	v_cmp_lt_u32_e32 vcc, v1, v2
	s_and_saveexec_b64 s[14:15], vcc
	s_cbranch_execz .LBB0_2733
	s_add_u32 s12, s78, 0x200
	s_addc_u32 s13, s79, 0
	s_mov_b32 s26, 1
	s_branch .LBB0_2726

.LBB0_2831:
	s_or_b64 exec, exec, s[6:7]
	v_cvt_f32_u32_e32 v3, v0
	s_waitcnt vmcnt(0)
	v_readfirstlane_b32 s4, v2
	s_add_u32 s6, s78, 0x3500
	s_addc_u32 s7, s79, 0
	v_rcp_iflag_f32_e32 v3, v3
	v_add_u32_e32 v1, s4, v1
	v_add_u32_e32 v4, 1, v1
	s_mov_b64 s[8:9], 0
	v_mul_f32_e32 v2, 0x4f7ffffe, v3
	v_cvt_u32_f32_e32 v2, v2
	v_sub_u32_e32 v3, 0, v0
	v_mul_lo_u32 v3, v3, v2
	v_mul_hi_u32 v3, v2, v3
	v_add_u32_e32 v2, v2, v3
	v_mul_hi_u32 v2, v1, v2
	v_mul_lo_u32 v3, v2, v0
	v_sub_u32_e32 v1, v1, v3
	v_add_u32_e32 v5, 1, v2
	v_cmp_ge_u32_e32 vcc, v1, v0
	v_sub_u32_e32 v3, v1, v0
	s_nop 0
	v_cndmask_b32_e32 v2, v2, v5, vcc
	v_cndmask_b32_e32 v1, v1, v3, vcc
	v_add_u32_e32 v3, 1, v2
	v_cmp_ge_u32_e32 vcc, v1, v0
	s_nop 1
	v_cndmask_b32_e32 v2, v2, v3, vcc
	v_mul_lo_u32 v1, v0, v2
	v_add_u32_e32 v0, v1, v0
	v_cmp_ne_u32_e32 vcc, v4, v0
	v_mov_b64_e32 v[0:1], s[6:7]
	s_and_saveexec_b64 s[4:5], vcc
	s_cbranch_execz .LBB0_2843
	v_mov_b32_e32 v0, 0
	global_load_dword v1, v0, s[6:7] offset:-256 sc1
	s_mov_b64 s[12:13], 0
	s_waitcnt vmcnt(0)
	v_mov_b32_e32 v238, 0x20004
	ds_read_b32 v238, v238
	s_waitcnt lgkmcnt(0)
	v_add_u32_e32 v2, 1, v2
	v_mul_lo_u32 v2, v2, v238
	v_cmp_lt_u32_e32 vcc, v1, v2
	s_and_saveexec_b64 s[10:11], vcc
	s_cbranch_execz .LBB0_2842
	s_add_u32 s8, s78, 0x200
	s_addc_u32 s9, s79, 0
	s_mov_b32 s22, 1
	s_branch .LBB0_2835
